# grid barriers: first workgroup of each XCD to arrive starts an early L2 writeback
# baseline (speedup 1.0000x reference)
.LBB0_97:
	s_or_b64 exec, exec, s[12:13]
	v_cvt_f32_u32_e32 v3, v0
	s_waitcnt vmcnt(0)
	v_readfirstlane_b32 s0, v2
	s_mov_b64 s[14:15], -1
	v_rcp_iflag_f32_e32 v3, v3
	v_add_u32_e32 v1, s0, v1
	v_add_u32_e32 v4, 1, v1
	s_load_dwordx2 s[0:1], s[80:81], 0xd0
	v_mul_f32_e32 v2, 0x4f7ffffe, v3
	v_cvt_u32_f32_e32 v2, v2
	v_sub_u32_e32 v3, 0, v0
	s_waitcnt lgkmcnt(0)
	s_add_u32 s12, s0, 0x33500
	v_mul_lo_u32 v3, v3, v2
	v_mul_hi_u32 v3, v2, v3
	v_add_u32_e32 v2, v2, v3
	v_mul_hi_u32 v2, v1, v2
	v_mul_lo_u32 v3, v2, v0
	v_sub_u32_e32 v1, v1, v3
	v_add_u32_e32 v5, 1, v2
	v_cmp_ge_u32_e32 vcc, v1, v0
	v_sub_u32_e32 v3, v1, v0
	s_addc_u32 s13, s1, 0
	v_cndmask_b32_e32 v2, v2, v5, vcc
	v_cndmask_b32_e32 v1, v1, v3, vcc
	v_add_u32_e32 v3, 1, v2
	v_cmp_ge_u32_e32 vcc, v1, v0
	s_nop 1
	v_cndmask_b32_e32 v2, v2, v3, vcc
	v_mul_lo_u32 v1, v0, v2
	v_add_u32_e32 v3, 1, v1
	v_cmp_eq_u32_e32 vcc, v4, v3
	s_cbranch_vccz .Lxs_nofirst_0
	buffer_wbl2 sc1
	s_waitcnt vmcnt(0)
.Lxs_nofirst_0:
	v_add_u32_e32 v0, v1, v0
	v_cmp_ne_u32_e32 vcc, v4, v0
	v_mov_b64_e32 v[0:1], s[12:13]
	s_and_saveexec_b64 s[10:11], vcc
	s_cbranch_execz .LBB0_109
	v_mov_b32_e32 v0, 0
	global_load_dword v1, v0, s[12:13] sc1
	s_mov_b64 s[18:19], 0
	s_waitcnt vmcnt(0)
	v_cmp_eq_u32_e32 vcc, v1, v2
	s_and_saveexec_b64 s[16:17], vcc
	s_cbranch_execz .LBB0_108
	s_load_dwordx2 s[0:1], s[80:81], 0xd0
	s_waitcnt lgkmcnt(0)
	s_add_u32 s14, s0, 0x30200
	s_addc_u32 s15, s1, 0
	s_mov_b32 s0, 1
	s_branch .LBB0_101

.LBB0_864:
	s_or_b64 exec, exec, s[12:13]
	v_cvt_f32_u32_e32 v3, v0
	s_waitcnt vmcnt(0)
	v_readfirstlane_b32 s0, v2
	s_mov_b64 s[14:15], -1
	v_rcp_iflag_f32_e32 v3, v3
	v_add_u32_e32 v1, s0, v1
	v_add_u32_e32 v4, 1, v1
	v_readlane_b32 s0, v255, 1
	v_mul_f32_e32 v2, 0x4f7ffffe, v3
	v_cvt_u32_f32_e32 v2, v2
	v_sub_u32_e32 v3, 0, v0
	v_readlane_b32 s1, v255, 2
	s_add_u32 s12, s0, 0x33500
	v_mul_lo_u32 v3, v3, v2
	v_mul_hi_u32 v3, v2, v3
	v_add_u32_e32 v2, v2, v3
	v_mul_hi_u32 v2, v1, v2
	v_mul_lo_u32 v3, v2, v0
	v_sub_u32_e32 v1, v1, v3
	v_add_u32_e32 v5, 1, v2
	v_cmp_ge_u32_e32 vcc, v1, v0
	v_sub_u32_e32 v3, v1, v0
	s_addc_u32 s13, s1, 0
	v_cndmask_b32_e32 v2, v2, v5, vcc
	v_cndmask_b32_e32 v1, v1, v3, vcc
	v_add_u32_e32 v3, 1, v2
	v_cmp_ge_u32_e32 vcc, v1, v0
	s_nop 1
	v_cndmask_b32_e32 v2, v2, v3, vcc
	v_mul_lo_u32 v1, v0, v2
	v_add_u32_e32 v3, 1, v1
	v_cmp_eq_u32_e32 vcc, v4, v3
	s_cbranch_vccz .Lxs_nofirst_4
	buffer_wbl2 sc1
	s_waitcnt vmcnt(0)
.Lxs_nofirst_4:
	v_add_u32_e32 v0, v1, v0
	v_cmp_ne_u32_e32 vcc, v4, v0
	v_mov_b64_e32 v[0:1], s[12:13]
	s_and_saveexec_b64 s[10:11], vcc
	s_cbranch_execz .LBB0_876
	v_mov_b32_e32 v0, 0
	global_load_dword v1, v0, s[12:13] sc1
	s_mov_b64 s[18:19], 0
	s_waitcnt vmcnt(0)
	v_cmp_eq_u32_e32 vcc, v1, v2
	s_and_saveexec_b64 s[16:17], vcc
	s_cbranch_execz .LBB0_875
	v_readlane_b32 s0, v255, 1
	v_readlane_b32 s1, v255, 2
	s_add_u32 s14, s0, 0x30200
	s_addc_u32 s15, s1, 0
	s_mov_b32 s0, 1
	s_branch .LBB0_868

.LBB0_1320:
	s_or_b64 exec, exec, s[10:11]
	v_cvt_f32_u32_e32 v3, v0
	s_waitcnt vmcnt(0)
	v_readfirstlane_b32 s0, v2
	s_mov_b64 s[12:13], -1
	v_rcp_iflag_f32_e32 v3, v3
	v_add_u32_e32 v1, s0, v1
	v_add_u32_e32 v4, 1, v1
	v_readlane_b32 s0, v255, 1
	v_mul_f32_e32 v2, 0x4f7ffffe, v3
	v_cvt_u32_f32_e32 v2, v2
	v_sub_u32_e32 v3, 0, v0
	v_readlane_b32 s1, v255, 2
	s_add_u32 s10, s0, 0x33500
	v_mul_lo_u32 v3, v3, v2
	v_mul_hi_u32 v3, v2, v3
	v_add_u32_e32 v2, v2, v3
	v_mul_hi_u32 v2, v1, v2
	v_mul_lo_u32 v3, v2, v0
	v_sub_u32_e32 v1, v1, v3
	v_add_u32_e32 v5, 1, v2
	v_cmp_ge_u32_e32 vcc, v1, v0
	v_sub_u32_e32 v3, v1, v0
	s_addc_u32 s11, s1, 0
	v_cndmask_b32_e32 v2, v2, v5, vcc
	v_cndmask_b32_e32 v1, v1, v3, vcc
	v_add_u32_e32 v3, 1, v2
	v_cmp_ge_u32_e32 vcc, v1, v0
	s_nop 1
	v_cndmask_b32_e32 v2, v2, v3, vcc
	v_mul_lo_u32 v1, v0, v2
	v_add_u32_e32 v3, 1, v1
	v_cmp_eq_u32_e32 vcc, v4, v3
	s_cbranch_vccz .Lxs_nofirst_7
	buffer_wbl2 sc1
	s_waitcnt vmcnt(0)
.Lxs_nofirst_7:
	v_add_u32_e32 v0, v1, v0
	v_cmp_ne_u32_e32 vcc, v4, v0
	v_mov_b64_e32 v[0:1], s[10:11]
	s_and_saveexec_b64 s[8:9], vcc
	s_cbranch_execz .LBB0_1332
	v_mov_b32_e32 v0, 0
	global_load_dword v1, v0, s[10:11] sc1
	s_mov_b64 s[16:17], 0
	s_waitcnt vmcnt(0)
	v_cmp_eq_u32_e32 vcc, v1, v2
	s_and_saveexec_b64 s[14:15], vcc
	s_cbranch_execz .LBB0_1331
	v_readlane_b32 s0, v255, 1
	v_readlane_b32 s1, v255, 2
	s_add_u32 s12, s0, 0x30200
	s_addc_u32 s13, s1, 0
	s_mov_b32 s0, 1
	s_branch .LBB0_1324
